# E22: P4 epilogue conv tap/bias loads issued at the top of the epilogue (latency under the scale section), on top of E21
# speedup vs baseline: 1.0249x; 1.0020x over previous
.LBB0_807:
	s_lshl_b32 s4, s4, 7
	v_readlane_b32 s98, v251, 42
	v_readlane_b32 s100, v251, 35
	v_readlane_b32 s101, v251, 36
	s_cmp_lt_u32 s98, 4
	s_cbranch_scc0 .Lprm4_skip
	v_mbcnt_lo_u32_b32 v231, -1, 0
	v_mbcnt_hi_u32_b32 v231, -1, v231
	s_lshl_b32 s99, s98, 6
	v_add_u32_e32 v231, s99, v231
	s_cmp_lt_u32 s98, 2
	s_cselect_b32 s99, 0, 0x2a80
	s_add_i32 s99, s99, s4
	v_add_u32_e32 v231, s99, v231
	v_lshlrev_b32_e32 v231, 2, v231
	global_load_dword v232, v231, s[100:101]
	s_add_u32 s98, s100, 0x15800
	s_addc_u32 s99, s101, 0
	global_load_dword v233, v231, s[98:99]
	s_add_u32 s98, s100, 0x2b000
	s_addc_u32 s99, s101, 0
	global_load_dword v234, v231, s[98:99]
	v_readlane_b32 s98, v251, 5
	v_readlane_b32 s99, v251, 6
	s_nop 4
	global_load_dword v235, v231, s[98:99]
.Lprm4_skip:
	s_ashr_i32 s5, s4, 31
	v_ashrrev_i32_e32 v147, 4, v128
	s_lshl_b64 s[6:7], s[4:5], 2
	v_lshlrev_b32_e32 v140, 3, v147
	s_add_u32 s6, s59, s6
	v_and_b32_e32 v191, 15, v128
	v_ashrrev_i32_e32 v141, 31, v140
	s_addc_u32 s7, s24, s7
	v_lshl_add_u32 v128, v191, 2, s25
	v_lshl_add_u64 v[132:133], v[140:141], 2, s[6:7]
	ds_read2_b32 v[144:145], v128 offset1:16
	ds_read2_b32 v[142:143], v128 offset0:32 offset1:48
	ds_read2_b32 v[138:139], v128 offset0:128 offset1:144
	ds_read2_b32 v[136:137], v128 offset0:160 offset1:176
	s_lshl_b32 s98, s69, 2
	s_add_i32 s98, s98, 0x21000
	v_lshl_add_u32 v230, v140, 2, s98
	ds_read_b128 v[128:131], v230
	v_cvt_f32_i32_e32 v85, v85
	v_cvt_f32_i32_e32 v84, v84
	v_cvt_f32_i32_e32 v89, v89
	v_cvt_f32_i32_e32 v88, v88
	v_cvt_f32_i32_e32 v87, v87
	v_cvt_f32_i32_e32 v86, v86
	v_cvt_f32_i32_e32 v93, v93
	v_cvt_f32_i32_e32 v92, v92
	v_cvt_f32_i32_e32 v91, v91
	v_cvt_f32_i32_e32 v90, v90
	s_waitcnt lgkmcnt(0)
	v_mov_b32_e32 v148, v145
	v_cvt_f32_i32_e32 v95, v95
	v_cvt_f32_i32_e32 v94, v94
	v_cvt_f32_i32_e32 v97, v97
	v_cvt_f32_i32_e32 v96, v96
	v_cvt_f32_i32_e32 v99, v99
	v_cvt_f32_i32_e32 v98, v98
	v_cvt_f32_i32_e32 v49, v49
	v_cvt_f32_i32_e32 v48, v48
	v_cvt_f32_i32_e32 v51, v51
	v_cvt_f32_i32_e32 v50, v50
	v_cvt_f32_i32_e32 v53, v53
	v_cvt_f32_i32_e32 v52, v52
	v_cvt_f32_i32_e32 v55, v55
	v_cvt_f32_i32_e32 v54, v54
	v_cvt_f32_i32_e32 v57, v57
	v_cvt_f32_i32_e32 v56, v56
	v_cvt_f32_i32_e32 v59, v59
	v_cvt_f32_i32_e32 v58, v58
	v_cvt_f32_i32_e32 v65, v65
	v_cvt_f32_i32_e32 v64, v64
	v_cvt_f32_i32_e32 v67, v67
	v_cvt_f32_i32_e32 v66, v66
	v_mov_b32_e32 v146, v137
	s_waitcnt lgkmcnt(0)
	v_pk_mul_f32 v[150:151], v[144:145], v[128:129] op_sel_hi:[0,1]
	v_pk_mul_f32 v[84:85], v[150:151], v[84:85]
	v_pk_mul_f32 v[150:151], v[148:149], v[128:129] op_sel_hi:[0,1]
	v_pk_mul_f32 v[134:135], v[144:145], v[130:131] op_sel_hi:[0,1]
	v_pk_mul_f32 v[88:89], v[150:151], v[88:89]
	v_pk_mul_f32 v[150:151], v[142:143], v[128:129] op_sel_hi:[0,1]
	v_pk_mul_f32 v[86:87], v[134:135], v[86:87]
	v_pk_mul_f32 v[134:135], v[148:149], v[130:131] op_sel_hi:[0,1]
	v_pk_mul_f32 v[92:93], v[150:151], v[92:93]
	v_mov_b32_e32 v150, v143
	v_pk_mul_f32 v[90:91], v[134:135], v[90:91]
	v_pk_mul_f32 v[134:135], v[142:143], v[130:131] op_sel_hi:[0,1]
	v_pk_mul_f32 v[152:153], v[150:151], v[128:129] op_sel_hi:[0,1]
	v_pk_mul_f32 v[94:95], v[134:135], v[94:95]
	v_pk_mul_f32 v[134:135], v[150:151], v[130:131] op_sel_hi:[0,1]
	v_pk_mul_f32 v[96:97], v[152:153], v[96:97]
	v_pk_mul_f32 v[152:153], v[138:139], v[128:129] op_sel_hi:[0,1]
	v_pk_mul_f32 v[98:99], v[134:135], v[98:99]
	v_pk_mul_f32 v[134:135], v[138:139], v[130:131] op_sel_hi:[0,1]
	v_pk_mul_f32 v[48:49], v[152:153], v[48:49]
	v_mov_b32_e32 v152, v139
	v_pk_mul_f32 v[50:51], v[134:135], v[50:51]
	v_pk_mul_f32 v[134:135], v[152:153], v[130:131] op_sel_hi:[0,1]
	v_pk_mul_f32 v[154:155], v[152:153], v[128:129] op_sel_hi:[0,1]
	v_pk_mul_f32 v[54:55], v[134:135], v[54:55]
	v_pk_mul_f32 v[52:53], v[154:155], v[52:53]
	v_pk_mul_f32 v[134:135], v[136:137], v[130:131] op_sel_hi:[0,1]
	v_pk_mul_f32 v[154:155], v[136:137], v[128:129] op_sel_hi:[0,1]
	v_pk_mul_f32 v[130:131], v[130:131], v[146:147] op_sel_hi:[1,0]
	v_pk_mul_f32 v[128:129], v[128:129], v[146:147] op_sel_hi:[1,0]
	v_pk_mul_f32 v[58:59], v[134:135], v[58:59]
	v_pk_mul_f32 v[56:57], v[154:155], v[56:57]
	v_pk_mul_f32 v[66:67], v[130:131], v[66:67]
	v_pk_mul_f32 v[64:65], v[128:129], v[64:65]
	s_nop 0
	ds_read_b128 v[128:131], v230 offset:16
	v_cvt_f32_i32_e32 v17, v17
	v_cvt_f32_i32_e32 v16, v16
	v_cvt_f32_i32_e32 v19, v19
	v_cvt_f32_i32_e32 v18, v18
	v_cvt_f32_i32_e32 v21, v21
	v_cvt_f32_i32_e32 v20, v20
	v_cvt_f32_i32_e32 v23, v23
	v_cvt_f32_i32_e32 v22, v22
	v_cvt_f32_i32_e32 v25, v25
	v_cvt_f32_i32_e32 v24, v24
	v_cvt_f32_i32_e32 v27, v27
	v_cvt_f32_i32_e32 v26, v26
	v_cvt_f32_i32_e32 v29, v29
	v_cvt_f32_i32_e32 v28, v28
	v_cvt_f32_i32_e32 v31, v31
	v_cvt_f32_i32_e32 v30, v30
	v_cvt_f32_i32_e32 v1, v1
	v_cvt_f32_i32_e32 v0, v0
	v_cvt_f32_i32_e32 v3, v3
	v_cvt_f32_i32_e32 v2, v2
	v_cvt_f32_i32_e32 v5, v5
	v_cvt_f32_i32_e32 v4, v4
	v_cvt_f32_i32_e32 v7, v7
	v_cvt_f32_i32_e32 v6, v6
	v_cvt_f32_i32_e32 v9, v9
	v_cvt_f32_i32_e32 v8, v8
	v_cvt_f32_i32_e32 v11, v11
	v_cvt_f32_i32_e32 v10, v10
	v_cvt_f32_i32_e32 v13, v13
	v_cvt_f32_i32_e32 v12, v12
	v_cvt_f32_i32_e32 v15, v15
	v_cvt_f32_i32_e32 v14, v14
	s_waitcnt lgkmcnt(0)
	v_pk_mul_f32 v[134:135], v[144:145], v[130:131] op_sel_hi:[0,1]
	v_pk_mul_f32 v[154:155], v[144:145], v[128:129] op_sel_hi:[0,1]
	v_pk_mul_f32 v[18:19], v[134:135], v[18:19]
	v_pk_mul_f32 v[16:17], v[154:155], v[16:17]
	v_pk_mul_f32 v[134:135], v[148:149], v[130:131] op_sel_hi:[0,1]
	v_pk_mul_f32 v[154:155], v[148:149], v[128:129] op_sel_hi:[0,1]
	v_pk_mul_f32 v[22:23], v[134:135], v[22:23]
	v_pk_mul_f32 v[20:21], v[154:155], v[20:21]
	v_pk_mul_f32 v[134:135], v[142:143], v[130:131] op_sel_hi:[0,1]
	v_pk_mul_f32 v[154:155], v[142:143], v[128:129] op_sel_hi:[0,1]
	v_pk_mul_f32 v[26:27], v[134:135], v[26:27]
	v_pk_mul_f32 v[24:25], v[154:155], v[24:25]
	v_pk_mul_f32 v[134:135], v[150:151], v[130:131] op_sel_hi:[0,1]
	v_pk_mul_f32 v[154:155], v[150:151], v[128:129] op_sel_hi:[0,1]
	v_pk_mul_f32 v[30:31], v[134:135], v[30:31]
	v_pk_mul_f32 v[28:29], v[154:155], v[28:29]
	v_pk_mul_f32 v[134:135], v[138:139], v[130:131] op_sel_hi:[0,1]
	v_pk_mul_f32 v[154:155], v[138:139], v[128:129] op_sel_hi:[0,1]
	v_pk_mul_f32 v[2:3], v[134:135], v[2:3]
	v_pk_mul_f32 v[0:1], v[154:155], v[0:1]
	v_pk_mul_f32 v[134:135], v[152:153], v[130:131] op_sel_hi:[0,1]
	v_pk_mul_f32 v[154:155], v[152:153], v[128:129] op_sel_hi:[0,1]
	v_pk_mul_f32 v[6:7], v[134:135], v[6:7]
	v_pk_mul_f32 v[4:5], v[154:155], v[4:5]
	v_pk_mul_f32 v[134:135], v[136:137], v[130:131] op_sel_hi:[0,1]
	v_pk_mul_f32 v[154:155], v[136:137], v[128:129] op_sel_hi:[0,1]
	v_pk_mul_f32 v[130:131], v[146:147], v[130:131] op_sel_hi:[0,1]
	v_pk_mul_f32 v[128:129], v[146:147], v[128:129] op_sel_hi:[0,1]
	v_pk_mul_f32 v[10:11], v[134:135], v[10:11]
	v_pk_mul_f32 v[8:9], v[154:155], v[8:9]
	v_pk_mul_f32 v[14:15], v[130:131], v[14:15]
	v_pk_mul_f32 v[12:13], v[128:129], v[12:13]
	s_nop 0
	s_mov_b32 s5, 0xa000
	v_add_co_u32_e32 v154, vcc, s5, v132
	v_cvt_f32_i32_e32 v125, v125
	s_nop 0
	v_addc_co_u32_e32 v155, vcc, 0, v133, vcc
	ds_read_b128 v[132:135], v230 offset:512
	v_cvt_f32_i32_e32 v124, v124
	v_cvt_f32_i32_e32 v127, v127
	v_cvt_f32_i32_e32 v126, v126
	v_cvt_f32_i32_e32 v121, v121
	v_cvt_f32_i32_e32 v120, v120
	v_cvt_f32_i32_e32 v123, v123
	v_cvt_f32_i32_e32 v122, v122
	v_cvt_f32_i32_e32 v117, v117
	v_cvt_f32_i32_e32 v116, v116
	v_cvt_f32_i32_e32 v119, v119
	v_cvt_f32_i32_e32 v118, v118
	v_cvt_f32_i32_e32 v113, v113
	v_cvt_f32_i32_e32 v112, v112
	v_cvt_f32_i32_e32 v115, v115
	v_cvt_f32_i32_e32 v114, v114
	v_cvt_f32_i32_e32 v109, v109
	v_cvt_f32_i32_e32 v108, v108
	v_cvt_f32_i32_e32 v111, v111
	v_cvt_f32_i32_e32 v110, v110
	v_cvt_f32_i32_e32 v105, v105
	v_cvt_f32_i32_e32 v104, v104
	v_cvt_f32_i32_e32 v107, v107
	v_cvt_f32_i32_e32 v106, v106
	v_cvt_f32_i32_e32 v103, v103
	v_cvt_f32_i32_e32 v102, v102
	v_cvt_f32_i32_e32 v101, v101
	v_cvt_f32_i32_e32 v100, v100
	v_cvt_f32_i32_e32 v77, v77
	v_cvt_f32_i32_e32 v76, v76
	v_cvt_f32_i32_e32 v79, v79
	v_cvt_f32_i32_e32 v78, v78
	s_waitcnt lgkmcnt(0)
	v_pk_mul_f32 v[128:129], v[144:145], v[134:135] op_sel_hi:[0,1]
	v_pk_mul_f32 v[156:157], v[144:145], v[132:133] op_sel_hi:[0,1]
	v_pk_mul_f32 v[130:131], v[128:129], v[126:127]
	v_pk_mul_f32 v[128:129], v[156:157], v[124:125]
	v_pk_mul_f32 v[124:125], v[148:149], v[134:135] op_sel_hi:[0,1]
	v_pk_mul_f32 v[156:157], v[148:149], v[132:133] op_sel_hi:[0,1]
	v_pk_mul_f32 v[126:127], v[124:125], v[122:123]
	v_pk_mul_f32 v[124:125], v[156:157], v[120:121]
	v_pk_mul_f32 v[120:121], v[142:143], v[134:135] op_sel_hi:[0,1]
	v_pk_mul_f32 v[156:157], v[142:143], v[132:133] op_sel_hi:[0,1]
	v_pk_mul_f32 v[122:123], v[120:121], v[118:119]
	v_pk_mul_f32 v[120:121], v[156:157], v[116:117]
	v_pk_mul_f32 v[116:117], v[150:151], v[134:135] op_sel_hi:[0,1]
	v_pk_mul_f32 v[156:157], v[150:151], v[132:133] op_sel_hi:[0,1]
	v_pk_mul_f32 v[118:119], v[116:117], v[114:115]
	v_pk_mul_f32 v[116:117], v[156:157], v[112:113]
	v_pk_mul_f32 v[112:113], v[138:139], v[134:135] op_sel_hi:[0,1]
	v_pk_mul_f32 v[156:157], v[138:139], v[132:133] op_sel_hi:[0,1]
	v_pk_mul_f32 v[114:115], v[112:113], v[110:111]
	v_pk_mul_f32 v[112:113], v[156:157], v[108:109]
	v_pk_mul_f32 v[108:109], v[152:153], v[134:135] op_sel_hi:[0,1]
	v_pk_mul_f32 v[156:157], v[152:153], v[132:133] op_sel_hi:[0,1]
	v_pk_mul_f32 v[110:111], v[108:109], v[106:107]
	v_pk_mul_f32 v[108:109], v[156:157], v[104:105]
	v_pk_mul_f32 v[104:105], v[136:137], v[134:135] op_sel_hi:[0,1]
	v_pk_mul_f32 v[106:107], v[136:137], v[132:133] op_sel_hi:[0,1]
	v_pk_mul_f32 v[102:103], v[104:105], v[102:103]
	v_pk_mul_f32 v[104:105], v[146:147], v[134:135] op_sel_hi:[0,1]
	v_pk_mul_f32 v[132:133], v[146:147], v[132:133] op_sel_hi:[0,1]
	v_pk_mul_f32 v[100:101], v[106:107], v[100:101]
	v_pk_mul_f32 v[106:107], v[104:105], v[78:79]
	v_pk_mul_f32 v[104:105], v[132:133], v[76:77]
	s_nop 0
	ds_read_b128 v[132:135], v230 offset:528
	v_cvt_f32_i32_e32 v69, v69
	v_cvt_f32_i32_e32 v68, v68
	v_cvt_f32_i32_e32 v71, v71
	v_cvt_f32_i32_e32 v70, v70
	v_cvt_f32_i32_e32 v61, v61
	v_cvt_f32_i32_e32 v60, v60
	v_cvt_f32_i32_e32 v63, v63
	v_cvt_f32_i32_e32 v62, v62
	v_cvt_f32_i32_e32 v45, v45
	v_cvt_f32_i32_e32 v44, v44
	v_cvt_f32_i32_e32 v47, v47
	v_cvt_f32_i32_e32 v46, v46
	v_cvt_f32_i32_e32 v41, v41
	v_cvt_f32_i32_e32 v40, v40
	v_cvt_f32_i32_e32 v43, v43
	v_cvt_f32_i32_e32 v42, v42
	v_cvt_f32_i32_e32 v33, v33
	v_cvt_f32_i32_e32 v32, v32
	v_cvt_f32_i32_e32 v35, v35
	v_cvt_f32_i32_e32 v34, v34
	v_cvt_f32_i32_e32 v37, v37
	v_cvt_f32_i32_e32 v36, v36
	v_cvt_f32_i32_e32 v39, v39
	v_cvt_f32_i32_e32 v38, v38
	s_waitcnt lgkmcnt(0)
	v_pk_mul_f32 v[76:77], v[144:145], v[134:135] op_sel_hi:[0,1]
	v_pk_mul_f32 v[144:145], v[144:145], v[132:133] op_sel_hi:[0,1]
	v_pk_mul_f32 v[78:79], v[76:77], v[70:71]
	v_pk_mul_f32 v[76:77], v[144:145], v[68:69]
	v_cvt_f32_i32_e32 v69, v73
	v_cvt_f32_i32_e32 v68, v72
	v_cvt_f32_i32_e32 v71, v75
	v_cvt_f32_i32_e32 v70, v74
	v_pk_mul_f32 v[72:73], v[148:149], v[134:135] op_sel_hi:[0,1]
	v_pk_mul_f32 v[144:145], v[148:149], v[132:133] op_sel_hi:[0,1]
	v_pk_mul_f32 v[74:75], v[72:73], v[70:71]
	v_pk_mul_f32 v[72:73], v[144:145], v[68:69]
	v_cvt_f32_i32_e32 v69, v81
	v_cvt_f32_i32_e32 v68, v80
	v_cvt_f32_i32_e32 v71, v83
	v_cvt_f32_i32_e32 v70, v82
	v_pk_mul_f32 v[80:81], v[142:143], v[134:135] op_sel_hi:[0,1]
	v_pk_mul_f32 v[82:83], v[142:143], v[132:133] op_sel_hi:[0,1]
	v_pk_mul_f32 v[68:69], v[82:83], v[68:69]
	v_pk_mul_f32 v[70:71], v[80:81], v[70:71]
	v_pk_mul_f32 v[80:81], v[150:151], v[134:135] op_sel_hi:[0,1]
	v_pk_mul_f32 v[82:83], v[150:151], v[132:133] op_sel_hi:[0,1]
	v_pk_mul_f32 v[62:63], v[80:81], v[62:63]
	v_pk_mul_f32 v[60:61], v[82:83], v[60:61]
	v_pk_mul_f32 v[80:81], v[138:139], v[134:135] op_sel_hi:[0,1]
	v_pk_mul_f32 v[82:83], v[138:139], v[132:133] op_sel_hi:[0,1]
	v_pk_mul_f32 v[46:47], v[80:81], v[46:47]
	v_pk_mul_f32 v[44:45], v[82:83], v[44:45]
	v_pk_mul_f32 v[80:81], v[152:153], v[134:135] op_sel_hi:[0,1]
	v_pk_mul_f32 v[82:83], v[152:153], v[132:133] op_sel_hi:[0,1]
	v_pk_mul_f32 v[42:43], v[80:81], v[42:43]
	v_pk_mul_f32 v[40:41], v[82:83], v[40:41]
	v_pk_mul_f32 v[80:81], v[136:137], v[134:135] op_sel_hi:[0,1]
	v_pk_mul_f32 v[82:83], v[136:137], v[132:133] op_sel_hi:[0,1]
	v_pk_mul_f32 v[34:35], v[80:81], v[34:35]
	v_pk_mul_f32 v[32:33], v[82:83], v[32:33]
	v_pk_mul_f32 v[80:81], v[146:147], v[134:135] op_sel_hi:[0,1]
	v_pk_mul_f32 v[82:83], v[146:147], v[132:133] op_sel_hi:[0,1]
	v_pk_mul_f32 v[38:39], v[80:81], v[38:39]
	v_pk_mul_f32 v[36:37], v[82:83], v[36:37]
	s_nop 0
	v_cmp_gt_i32_e32 vcc, s94, v149
	s_and_saveexec_b64 s[6:7], vcc
	s_cbranch_execz .LBB0_809
	s_movk_i32 s5, 0x80
	v_cmp_gt_i32_e32 vcc, s5, v149
	s_add_i32 s5, s4, 0x2a80
	v_mov_b32_e32 v80, s5
	v_mov_b32_e32 v81, s4
	v_cndmask_b32_e32 v80, v80, v81, vcc
	v_add_u32_e32 v80, v80, v149
	v_ashrrev_i32_e32 v81, 31, v80
	v_readlane_b32 s8, v251, 21
	v_lshlrev_b64 v[80:81], 2, v[80:81]
	v_readlane_b32 s22, v251, 35
	v_readlane_b32 s23, v251, 36
	v_lshl_add_u32 v132, v149, 2, 0
	v_readlane_b32 s9, v251, 22
	v_lshl_add_u64 v[82:83], s[22:23], 0, v[80:81]
	v_readlane_b32 s10, v251, 23
	v_readlane_b32 s11, v251, 24
	v_readlane_b32 s12, v251, 25
	v_readlane_b32 s13, v251, 26
	v_readlane_b32 s14, v251, 27
	v_readlane_b32 s15, v251, 28
	v_readlane_b32 s16, v251, 29
	v_readlane_b32 s17, v251, 30
	v_readlane_b32 s18, v251, 31
	v_readlane_b32 s19, v251, 32
	v_readlane_b32 s20, v251, 33
	v_readlane_b32 s21, v251, 34
	v_add_u32_e32 v135, 0x20000, v132
	v_add_co_u32_e32 v132, vcc, 0x15000, v82
	v_readlane_b32 s8, v251, 5
	s_nop 0
	v_addc_co_u32_e32 v133, vcc, 0, v83, vcc
	v_readlane_b32 s9, v251, 6
	v_add_co_u32_e32 v82, vcc, 0x2b000, v82
	v_lshl_add_u64 v[80:81], s[8:9], 0, v[80:81]
	s_nop 0
	v_addc_co_u32_e32 v83, vcc, 0, v83, vcc
	v_readlane_b32 s10, v251, 7
	v_readlane_b32 s11, v251, 8
	v_readlane_b32 s12, v251, 9
	v_readlane_b32 s13, v251, 10
	v_readlane_b32 s14, v251, 11
	v_readlane_b32 s15, v251, 12
	v_readlane_b32 s16, v251, 13
	v_readlane_b32 s17, v251, 14
	v_readlane_b32 s18, v251, 15
	v_readlane_b32 s19, v251, 16
	v_readlane_b32 s20, v251, 17
	v_readlane_b32 s21, v251, 18
	v_readlane_b32 s22, v251, 19
	v_readlane_b32 s23, v251, 20
	s_waitcnt vmcnt(0)
	ds_write2st64_b32 v135, v232, v233 offset1:4
	s_waitcnt vmcnt(0)
	ds_write2st64_b32 v135, v234, v235 offset0:8 offset1:12
